# ffn fixup phase rewritten by hand: per-thread fixed channel block, conv weights loaded once, all UB loads of 3 items in flight together (on top of norm rewrite)
# speedup vs baseline: 1.0110x; 1.0041x over previous
; DI void ffn_fixup_phase(const Args& A, int wave_s, int l, int rows) {
;     const Ctx C = make_ctx(A, wave_s);
;     const float* cw = C.conv_w + (size_t)l * 3 * 5632; const float* cb = C.conv_b + (size_t)l * 5632;
;     const bf16* UB = C.ACT;
;     bf16* ACTF = C.U;
;     const int nkb = rows / 64, total = nkb * 2 * 352;
;     for (int e = blockIdx.x * 512 + C.tid; e < total; e += gridDim.x * 512) {
;         const int c8 = (e % 352) * 8, rs = e / 352, side = rs & 1, kb = rs >> 1;
;         const int R = kb * 64 + (side ? 63 : 0);
;         bool first, last;
;         if (R < NLAT) { first = (R & 8191) == 0; last = (R & 8191) == 8191; } else { first = ((R - NLAT) & 255) == 0; last = ((R - NLAT) & 255) == 255; }
;         const v4u z = {0u, 0u, 0u, 0u};
;         const bf16* pp = side ? UB + (size_t)((kb * 4 + 2) * 2) * 2816 : UB + (size_t)(((kb - 1) * 4 + 3) * 2) * 2816;
;         const bf16* pc = UB + (size_t)((kb * 4 + (side ? 3 : 0)) * 2) * 2816;
;         const bf16* pn = side ? UB + (size_t)(((kb + 1) * 4 + 0) * 2) * 2816 : UB + (size_t)((kb * 4 + 1) * 2) * 2816;
;         const bool zp = (!side) && first, zn = side && last;
;         const v4u a0 = zp ? z : *(const v4u*)(pp + c8), a1 = *(const v4u*)(pc + c8), a2 = zn ? z : *(const v4u*)(pn + c8);
;         const v4u b0 = zp ? z : *(const v4u*)(pp + 2816 + c8), b1 = *(const v4u*)(pc + 2816 + c8), b2 = zn ? z : *(const v4u*)(pn + 2816 + c8);
.LBB0_696:
	s_or_b64 exec, exec, s[4:5]
	s_lshr_b32 s2, s42, 5
	v_readlane_b32 s4, v253, 37
	s_waitcnt lgkmcnt(0)
	s_barrier
	v_mbcnt_lo_u32_b32 v0, -1, 0
	v_mbcnt_hi_u32_b32 v0, -1, v0
	v_mbcnt_lo_u32_b32 v0, -1, 0
	v_mbcnt_hi_u32_b32 v0, -1, v0
	v_readlane_b32 s6, v255, 32
	s_lshr_b32 s5, s94, 6
	s_lshl_b32 s7, s65, 3
	s_add_u32 s5, s5, s7
	s_cmp_ge_u32 s5, 2046
	s_cbranch_scc1 .Lfix_f_done
	s_lshr_b32 s6, s6, 10
	s_lshl_b32 s7, s5, 6
	v_add_u32_e32 v224, s7, v0
	v_mov_b32_e32 v225, 0xba2e8c
	v_mul_hi_u32 v225, v224, v225
	v_mov_b32_e32 v226, 0x160
	v_mul_lo_u32 v226, v225, v226
	v_sub_u32_e32 v226, v224, v226
	v_lshlrev_b32_e32 v227, 4, v226
	v_readlane_b32 s8, v252, 25
	v_readlane_b32 s9, v252, 26
	v_readlane_b32 s24, v252, 27
	v_readlane_b32 s25, v252, 28
	s_mul_i32 s7, s6, 0x10800
	s_nop 0
	s_add_u32 s8, s8, s7
	s_addc_u32 s9, s9, 0
	s_mul_i32 s7, s6, 0x5800
	s_add_u32 s24, s24, s7
	s_addc_u32 s25, s25, 0
	v_lshlrev_b32_e32 v228, 5, v226
	s_add_u32 s26, s8, 0x0
	s_addc_u32 s27, s9, 0
	global_load_dwordx4 v[4:7], v228, s[26:27]
	global_load_dwordx4 v[8:11], v228, s[26:27] offset:16
	s_add_u32 s26, s8, 0x5800
	s_addc_u32 s27, s9, 0
	global_load_dwordx4 v[12:15], v228, s[26:27]
	global_load_dwordx4 v[24:27], v228, s[26:27] offset:16
	s_add_u32 s26, s8, 0xb000
	s_addc_u32 s27, s9, 0
	global_load_dwordx4 v[28:31], v228, s[26:27]
	global_load_dwordx4 v[32:35], v228, s[26:27] offset:16
	s_add_u32 s26, s8, 0x2c00
	s_addc_u32 s27, s9, 0
	global_load_dwordx4 v[64:67], v228, s[26:27]
	global_load_dwordx4 v[68:71], v228, s[26:27] offset:16
	s_add_u32 s26, s8, 0x8400
	s_addc_u32 s27, s9, 0
	global_load_dwordx4 v[72:75], v228, s[26:27]
	global_load_dwordx4 v[80:83], v228, s[26:27] offset:16
	s_add_u32 s26, s8, 0xdc00
	s_addc_u32 s27, s9, 0
	global_load_dwordx4 v[84:87], v228, s[26:27]
	global_load_dwordx4 v[88:91], v228, s[26:27] offset:16
	s_add_u32 s26, s24, 0x0
	s_addc_u32 s27, s25, 0
	global_load_dwordx4 v[36:39], v228, s[26:27]
	global_load_dwordx4 v[40:43], v228, s[26:27] offset:16
	s_add_u32 s26, s24, 0x2c00
	s_addc_u32 s27, s25, 0
	global_load_dwordx4 v[92:95], v228, s[26:27]
	global_load_dwordx4 v[96:99], v228, s[26:27] offset:16
	s_add_u32 s28, s88, 0x171fd400
	s_addc_u32 s29, s89, 0
	s_add_u32 s30, s88, 0xbc00000
	s_addc_u32 s31, s89, 0
	v_mov_b32_e32 v229, v225
	v_and_b32_e32 v184, 1, v229
	v_lshrrev_b32_e32 v185, 1, v229
	v_lshlrev_b32_e32 v185, 2, v185
	v_mad_u32_u24 v185, v184, 3, v185
	v_mov_b32_e32 v184, 0x2c00
	v_mul_lo_u32 v185, v185, v184
	v_add_u32_e32 v185, v185, v227
	v_mov_b32_e32 v177, 0
	v_mov_b32_e32 v176, v185
	v_lshl_add_u64 v[176:177], v[176:177], 0, s[28:29]
	global_load_dwordx4 v[100:103], v[176:177], off
	s_mov_b64 s[26:27], 5632
	v_lshl_add_u64 v[178:179], v[176:177], 0, s[26:27]
	global_load_dwordx4 v[104:107], v[178:179], off
	s_mov_b64 s[26:27], 11264
	v_lshl_add_u64 v[178:179], v[176:177], 0, s[26:27]
	global_load_dwordx4 v[108:111], v[178:179], off
	s_mov_b64 s[26:27], 16896
	v_lshl_add_u64 v[178:179], v[176:177], 0, s[26:27]
	global_load_dwordx4 v[112:115], v[178:179], off
	s_mov_b64 s[26:27], 22528
	v_lshl_add_u64 v[178:179], v[176:177], 0, s[26:27]
	global_load_dwordx4 v[116:119], v[178:179], off
	s_mov_b64 s[26:27], 28160
	v_lshl_add_u64 v[178:179], v[176:177], 0, s[26:27]
	global_load_dwordx4 v[120:123], v[178:179], off
	v_add_u32_e32 v230, 372, v225
	v_and_b32_e32 v184, 1, v230
	v_lshrrev_b32_e32 v185, 1, v230
	v_lshlrev_b32_e32 v185, 2, v185
	v_mad_u32_u24 v185, v184, 3, v185
	v_mov_b32_e32 v184, 0x2c00
	v_mul_lo_u32 v185, v185, v184
	v_add_u32_e32 v185, v185, v227
	v_mov_b32_e32 v177, 0
	v_mov_b32_e32 v176, v185
	v_lshl_add_u64 v[176:177], v[176:177], 0, s[28:29]
	global_load_dwordx4 v[124:127], v[176:177], off
	s_mov_b64 s[26:27], 5632
	v_lshl_add_u64 v[178:179], v[176:177], 0, s[26:27]
	global_load_dwordx4 v[128:131], v[178:179], off
	s_mov_b64 s[26:27], 11264
	v_lshl_add_u64 v[178:179], v[176:177], 0, s[26:27]
	global_load_dwordx4 v[132:135], v[178:179], off
	s_mov_b64 s[26:27], 16896
	v_lshl_add_u64 v[178:179], v[176:177], 0, s[26:27]
	global_load_dwordx4 v[136:139], v[178:179], off
	s_mov_b64 s[26:27], 22528
	v_lshl_add_u64 v[178:179], v[176:177], 0, s[26:27]
	global_load_dwordx4 v[140:143], v[178:179], off
	s_mov_b64 s[26:27], 28160
	v_lshl_add_u64 v[178:179], v[176:177], 0, s[26:27]
	global_load_dwordx4 v[144:147], v[178:179], off
	v_add_u32_e32 v231, 744, v225
	v_and_b32_e32 v184, 1, v231
	v_lshrrev_b32_e32 v185, 1, v231
	v_lshlrev_b32_e32 v185, 2, v185
	v_mad_u32_u24 v185, v184, 3, v185
	v_mov_b32_e32 v184, 0x2c00
	v_mul_lo_u32 v185, v185, v184
	v_add_u32_e32 v185, v185, v227
	v_mov_b32_e32 v177, 0
	v_mov_b32_e32 v176, v185
	v_lshl_add_u64 v[176:177], v[176:177], 0, s[28:29]
	global_load_dwordx4 v[148:151], v[176:177], off
	s_mov_b64 s[26:27], 5632
	v_lshl_add_u64 v[178:179], v[176:177], 0, s[26:27]
	global_load_dwordx4 v[152:155], v[178:179], off
	s_mov_b64 s[26:27], 11264
	v_lshl_add_u64 v[178:179], v[176:177], 0, s[26:27]
	global_load_dwordx4 v[156:159], v[178:179], off
	s_mov_b64 s[26:27], 16896
	v_lshl_add_u64 v[178:179], v[176:177], 0, s[26:27]
	global_load_dwordx4 v[164:167], v[178:179], off
	s_mov_b64 s[26:27], 22528
	v_lshl_add_u64 v[178:179], v[176:177], 0, s[26:27]
	global_load_dwordx4 v[168:171], v[178:179], off
	s_mov_b64 s[26:27], 28160
	v_lshl_add_u64 v[178:179], v[176:177], 0, s[26:27]
	global_load_dwordx4 v[172:175], v[178:179], off
	s_mul_i32 s7, s42, 11
	s_mov_b32 s10, 0x7fff
	s_mov_b32 s11, 0xffff0000
	s_waitcnt vmcnt(12)
; DI void ffn_fixup_phase(const Args& A, int wave_s, int l, int rows) {
;     ...
;         const int c8 = (e % 352) * 8, rs = e / 352, side = rs & 1, kb = rs >> 1;
;         const int R = kb * 64 + (side ? 63 : 0);
;         bool first, last;
;         if (R < NLAT) { first = (R & 8191) == 0; last = (R & 8191) == 8191; } else { first = ((R - NLAT) & 255) == 0; last = ((R - NLAT) & 255) == 255; }
;         const v4u z = {0u, 0u, 0u, 0u};
;         const bf16* pp = side ? UB + (size_t)((kb * 4 + 2) * 2) * 2816 : UB + (size_t)(((kb - 1) * 4 + 3) * 2) * 2816;
;         const bf16* pc = UB + (size_t)((kb * 4 + (side ? 3 : 0)) * 2) * 2816;
;         const bf16* pn = side ? UB + (size_t)(((kb + 1) * 4 + 0) * 2) * 2816 : UB + (size_t)((kb * 4 + 1) * 2) * 2816;
;         const bool zp = (!side) && first, zn = side && last;
;         const v4u a0 = zp ? z : *(const v4u*)(pp + c8), a1 = *(const v4u*)(pc + c8), a2 = zn ? z : *(const v4u*)(pn + c8);
;         const v4u b0 = zp ? z : *(const v4u*)(pp + 2816 + c8), b1 = *(const v4u*)(pc + 2816 + c8), b2 = zn ? z : *(const v4u*)(pn + 2816 + c8);
;         unsigned res[4];
; #pragma unroll
;         for (int q = 0; q < 4; ++q) {
;             float r2[2];
; #pragma unroll
;             for (int hlf = 0; hlf < 2; ++hlf) {
;                 const int i = c8 + 2 * q + hlf;
;                 const float ua0 = hlf ? __builtin_bit_cast(float, a0[q] & 0xffff0000u) : __builtin_bit_cast(float, a0[q] << 16);
;                 const float ua1 = hlf ? __builtin_bit_cast(float, a1[q] & 0xffff0000u) : __builtin_bit_cast(float, a1[q] << 16);
;                 const float ua2 = hlf ? __builtin_bit_cast(float, a2[q] & 0xffff0000u) : __builtin_bit_cast(float, a2[q] << 16);
;                 const float ub0 = hlf ? __builtin_bit_cast(float, b0[q] & 0xffff0000u) : __builtin_bit_cast(float, b0[q] << 16);
;                 const float ub1 = hlf ? __builtin_bit_cast(float, b1[q] & 0xffff0000u) : __builtin_bit_cast(float, b1[q] << 16);
;                 const float ub2 = hlf ? __builtin_bit_cast(float, b2[q] & 0xffff0000u) : __builtin_bit_cast(float, b2[q] << 16);
;                 const float ya = cb[i] + ua0 * cw[i] + ua1 * cw[5632 + i] + ua2 * cw[2 * 5632 + i];
;                 const float yv = cb[2816 + i] + ub0 * cw[2816 + i] + ub1 * cw[5632 + 2816 + i] + ub2 * cw[2 * 5632 + 2816 + i];
;                 r2[hlf] = silu_f(ya) * yv;
;             }
	v_and_b32_e32 v188, 1, v229
	v_lshrrev_b32_e32 v190, 1, v229
	v_lshlrev_b32_e32 v190, 6, v190
	v_mad_u32_u24 v190, v188, 63, v190
	v_mov_b32_e32 v191, 0xff
	v_mov_b32_e32 v189, 0x1fff
	v_cmp_gt_u32_e32 vcc, 0x8000, v190
	s_nop 1
	v_cndmask_b32_e32 v191, v191, v189, vcc
	v_and_b32_e32 v189, v190, v191
	v_or_b32_e32 v192, v189, v188
	v_cmp_eq_u32_e32 vcc, 0, v192
	s_nop 1
	v_cndmask_b32_e64 v100, v100, 0, vcc
	v_cndmask_b32_e64 v101, v101, 0, vcc
	v_cndmask_b32_e64 v102, v102, 0, vcc
	v_cndmask_b32_e64 v103, v103, 0, vcc
	v_cndmask_b32_e64 v104, v104, 0, vcc
	v_cndmask_b32_e64 v105, v105, 0, vcc
	v_cndmask_b32_e64 v106, v106, 0, vcc
	v_cndmask_b32_e64 v107, v107, 0, vcc
	v_cmp_eq_u32_e64 s[26:27], v189, v191
	v_cmp_eq_u32_e32 vcc, 1, v188
	s_nop 1
	s_and_b64 vcc, vcc, s[26:27]
	s_nop 1
	v_cndmask_b32_e64 v116, v116, 0, vcc
	v_cndmask_b32_e64 v117, v117, 0, vcc
	v_cndmask_b32_e64 v118, v118, 0, vcc
	v_cndmask_b32_e64 v119, v119, 0, vcc
	v_cndmask_b32_e64 v120, v120, 0, vcc
	v_cndmask_b32_e64 v121, v121, 0, vcc
	v_cndmask_b32_e64 v122, v122, 0, vcc
	v_cndmask_b32_e64 v123, v123, 0, vcc
	v_lshlrev_b32_e32 v204, 16, v100
	v_lshlrev_b32_e32 v205, 16, v108
	v_lshlrev_b32_e32 v206, 16, v116
	v_fma_f32 v200, v4, v204, v36
	v_fma_f32 v200, v12, v205, v200
	v_fma_f32 v200, v28, v206, v200
	v_lshlrev_b32_e32 v204, 16, v104
	v_lshlrev_b32_e32 v205, 16, v112
	v_lshlrev_b32_e32 v206, 16, v120
	v_fma_f32 v201, v64, v204, v92
	v_fma_f32 v201, v72, v205, v201
	v_fma_f32 v201, v84, v206, v201
	v_mul_f32_e32 v208, 0xbfb8aa3b, v200
	v_exp_f32_e32 v208, v208
	s_nop 0
	v_add_f32_e32 v209, 1.0, v208
	v_div_scale_f32 v210, s[26:27], v209, v209, v200
	v_rcp_f32_e32 v211, v210
	s_nop 0
	v_fma_f32 v212, -v210, v211, 1.0
	v_fmac_f32_e32 v211, v212, v211
	v_div_scale_f32 v213, vcc, v200, v209, v200
	v_mul_f32_e32 v214, v213, v211
	v_fma_f32 v215, -v210, v214, v213
	v_fmac_f32_e32 v214, v215, v211
	v_fma_f32 v210, -v210, v214, v213
	v_div_fmas_f32 v210, v210, v211, v214
	v_div_fixup_f32 v210, v210, v209, v200
	v_mul_f32_e32 v216, v210, v201
	v_and_b32_e32 v204, 0xffff0000, v100
	v_and_b32_e32 v205, 0xffff0000, v108
	v_and_b32_e32 v206, 0xffff0000, v116
	v_fma_f32 v200, v5, v204, v37
	v_fma_f32 v200, v13, v205, v200
	v_fma_f32 v200, v29, v206, v200
	v_and_b32_e32 v204, 0xffff0000, v104
	v_and_b32_e32 v205, 0xffff0000, v112
	v_and_b32_e32 v206, 0xffff0000, v120
	v_fma_f32 v201, v65, v204, v93
	v_fma_f32 v201, v73, v205, v201
	v_fma_f32 v201, v85, v206, v201
	v_mul_f32_e32 v208, 0xbfb8aa3b, v200
	v_exp_f32_e32 v208, v208
	s_nop 0
	v_add_f32_e32 v209, 1.0, v208
	v_div_scale_f32 v210, s[26:27], v209, v209, v200
	v_rcp_f32_e32 v211, v210
	s_nop 0
	v_fma_f32 v212, -v210, v211, 1.0
	v_fmac_f32_e32 v211, v212, v211
	v_div_scale_f32 v213, vcc, v200, v209, v200
	v_mul_f32_e32 v214, v213, v211
	v_fma_f32 v215, -v210, v214, v213
	v_fmac_f32_e32 v214, v215, v211
	v_fma_f32 v210, -v210, v214, v213
	v_div_fmas_f32 v210, v210, v211, v214
	v_div_fixup_f32 v210, v210, v209, v200
	v_mul_f32_e32 v217, v210, v201
	v_bfe_u32 v220, v216, 16, 1
	v_bfe_u32 v221, v217, 16, 1
	v_add3_u32 v220, v216, v220, s10
	v_add3_u32 v221, v217, v221, s10
	v_lshrrev_b32_e32 v220, 16, v220
	v_and_or_b32 v196, v221, s11, v220
	v_lshlrev_b32_e32 v204, 16, v101
	v_lshlrev_b32_e32 v205, 16, v109
	v_lshlrev_b32_e32 v206, 16, v117
	v_fma_f32 v200, v6, v204, v38
	v_fma_f32 v200, v14, v205, v200
	v_fma_f32 v200, v30, v206, v200
	v_lshlrev_b32_e32 v204, 16, v105
	v_lshlrev_b32_e32 v205, 16, v113
	v_lshlrev_b32_e32 v206, 16, v121
	v_fma_f32 v201, v66, v204, v94
	v_fma_f32 v201, v74, v205, v201
	v_fma_f32 v201, v86, v206, v201
	v_mul_f32_e32 v208, 0xbfb8aa3b, v200
	v_exp_f32_e32 v208, v208
	s_nop 0
	v_add_f32_e32 v209, 1.0, v208
	v_div_scale_f32 v210, s[26:27], v209, v209, v200
	v_rcp_f32_e32 v211, v210
	s_nop 0
	v_fma_f32 v212, -v210, v211, 1.0
	v_fmac_f32_e32 v211, v212, v211
	v_div_scale_f32 v213, vcc, v200, v209, v200
	v_mul_f32_e32 v214, v213, v211
	v_fma_f32 v215, -v210, v214, v213
	v_fmac_f32_e32 v214, v215, v211
	v_fma_f32 v210, -v210, v214, v213
	v_div_fmas_f32 v210, v210, v211, v214
	v_div_fixup_f32 v210, v210, v209, v200
	v_mul_f32_e32 v216, v210, v201
	v_and_b32_e32 v204, 0xffff0000, v101
	v_and_b32_e32 v205, 0xffff0000, v109
	v_and_b32_e32 v206, 0xffff0000, v117
	v_fma_f32 v200, v7, v204, v39
	v_fma_f32 v200, v15, v205, v200
	v_fma_f32 v200, v31, v206, v200
	v_and_b32_e32 v204, 0xffff0000, v105
	v_and_b32_e32 v205, 0xffff0000, v113
	v_and_b32_e32 v206, 0xffff0000, v121
	v_fma_f32 v201, v67, v204, v95
	v_fma_f32 v201, v75, v205, v201
	v_fma_f32 v201, v87, v206, v201
	v_mul_f32_e32 v208, 0xbfb8aa3b, v200
	v_exp_f32_e32 v208, v208
	s_nop 0
	v_add_f32_e32 v209, 1.0, v208
	v_div_scale_f32 v210, s[26:27], v209, v209, v200
	v_rcp_f32_e32 v211, v210
	s_nop 0
	v_fma_f32 v212, -v210, v211, 1.0
	v_fmac_f32_e32 v211, v212, v211
	v_div_scale_f32 v213, vcc, v200, v209, v200
	v_mul_f32_e32 v214, v213, v211
	v_fma_f32 v215, -v210, v214, v213
	v_fmac_f32_e32 v214, v215, v211
	v_fma_f32 v210, -v210, v214, v213
	v_div_fmas_f32 v210, v210, v211, v214
	v_div_fixup_f32 v210, v210, v209, v200
	v_mul_f32_e32 v217, v210, v201
	v_bfe_u32 v220, v216, 16, 1
	v_bfe_u32 v221, v217, 16, 1
	v_add3_u32 v220, v216, v220, s10
	v_add3_u32 v221, v217, v221, s10
	v_lshrrev_b32_e32 v220, 16, v220
	v_and_or_b32 v197, v221, s11, v220
	v_lshlrev_b32_e32 v204, 16, v102
	v_lshlrev_b32_e32 v205, 16, v110
	v_lshlrev_b32_e32 v206, 16, v118
	v_fma_f32 v200, v8, v204, v40
	v_fma_f32 v200, v24, v205, v200
	v_fma_f32 v200, v32, v206, v200
	v_lshlrev_b32_e32 v204, 16, v106
	v_lshlrev_b32_e32 v205, 16, v114
	v_lshlrev_b32_e32 v206, 16, v122
; DI unsigned pk2(float lo, float hi) { return f2bf(lo) | (f2bf(hi) << 16); }
; DI float silu_f(float x) { return x / (1.f + __expf(-x)); }
; DI void ffn_fixup_phase(const Args& A, int wave_s, int l, int rows) {
;     ...
;             for (int hlf = 0; hlf < 2; ++hlf) {
;                 const int i = c8 + 2 * q + hlf;
;                 const float ua0 = hlf ? __builtin_bit_cast(float, a0[q] & 0xffff0000u) : __builtin_bit_cast(float, a0[q] << 16);
;                 const float ua1 = hlf ? __builtin_bit_cast(float, a1[q] & 0xffff0000u) : __builtin_bit_cast(float, a1[q] << 16);
;                 const float ua2 = hlf ? __builtin_bit_cast(float, a2[q] & 0xffff0000u) : __builtin_bit_cast(float, a2[q] << 16);
;                 const float ub0 = hlf ? __builtin_bit_cast(float, b0[q] & 0xffff0000u) : __builtin_bit_cast(float, b0[q] << 16);
;                 const float ub1 = hlf ? __builtin_bit_cast(float, b1[q] & 0xffff0000u) : __builtin_bit_cast(float, b1[q] << 16);
;                 const float ub2 = hlf ? __builtin_bit_cast(float, b2[q] & 0xffff0000u) : __builtin_bit_cast(float, b2[q] << 16);
;                 const float ya = cb[i] + ua0 * cw[i] + ua1 * cw[5632 + i] + ua2 * cw[2 * 5632 + i];
;                 const float yv = cb[2816 + i] + ub0 * cw[2816 + i] + ub1 * cw[5632 + 2816 + i] + ub2 * cw[2 * 5632 + 2816 + i];
;                 r2[hlf] = silu_f(ya) * yv;
;             }
;             res[q] = pk2(r2[0], r2[1]);
;         }
;         v4u o; o.x = res[0]; o.y = res[1]; o.z = res[2]; o.w = res[3];
;         *(v4u*)(ACTF + (size_t)R * 2816 + c8) = o;
	v_fma_f32 v201, v68, v204, v96
	v_fma_f32 v201, v80, v205, v201
	v_fma_f32 v201, v88, v206, v201
	v_mul_f32_e32 v208, 0xbfb8aa3b, v200
	v_exp_f32_e32 v208, v208
	s_nop 0
	v_add_f32_e32 v209, 1.0, v208
	v_div_scale_f32 v210, s[26:27], v209, v209, v200
	v_rcp_f32_e32 v211, v210
	s_nop 0
	v_fma_f32 v212, -v210, v211, 1.0
	v_fmac_f32_e32 v211, v212, v211
	v_div_scale_f32 v213, vcc, v200, v209, v200
	v_mul_f32_e32 v214, v213, v211
	v_fma_f32 v215, -v210, v214, v213
	v_fmac_f32_e32 v214, v215, v211
	v_fma_f32 v210, -v210, v214, v213
	v_div_fmas_f32 v210, v210, v211, v214
	v_div_fixup_f32 v210, v210, v209, v200
	v_mul_f32_e32 v216, v210, v201
	v_and_b32_e32 v204, 0xffff0000, v102
	v_and_b32_e32 v205, 0xffff0000, v110
	v_and_b32_e32 v206, 0xffff0000, v118
	v_fma_f32 v200, v9, v204, v41
	v_fma_f32 v200, v25, v205, v200
	v_fma_f32 v200, v33, v206, v200
	v_and_b32_e32 v204, 0xffff0000, v106
	v_and_b32_e32 v205, 0xffff0000, v114
	v_and_b32_e32 v206, 0xffff0000, v122
	v_fma_f32 v201, v69, v204, v97
	v_fma_f32 v201, v81, v205, v201
	v_fma_f32 v201, v89, v206, v201
	v_mul_f32_e32 v208, 0xbfb8aa3b, v200
	v_exp_f32_e32 v208, v208
	s_nop 0
	v_add_f32_e32 v209, 1.0, v208
	v_div_scale_f32 v210, s[26:27], v209, v209, v200
	v_rcp_f32_e32 v211, v210
	s_nop 0
	v_fma_f32 v212, -v210, v211, 1.0
	v_fmac_f32_e32 v211, v212, v211
	v_div_scale_f32 v213, vcc, v200, v209, v200
	v_mul_f32_e32 v214, v213, v211
	v_fma_f32 v215, -v210, v214, v213
	v_fmac_f32_e32 v214, v215, v211
	v_fma_f32 v210, -v210, v214, v213
	v_div_fmas_f32 v210, v210, v211, v214
	v_div_fixup_f32 v210, v210, v209, v200
	v_mul_f32_e32 v217, v210, v201
	v_bfe_u32 v220, v216, 16, 1
	v_bfe_u32 v221, v217, 16, 1
	v_add3_u32 v220, v216, v220, s10
	v_add3_u32 v221, v217, v221, s10
	v_lshrrev_b32_e32 v220, 16, v220
	v_and_or_b32 v198, v221, s11, v220
	v_lshlrev_b32_e32 v204, 16, v103
	v_lshlrev_b32_e32 v205, 16, v111
	v_lshlrev_b32_e32 v206, 16, v119
	v_fma_f32 v200, v10, v204, v42
	v_fma_f32 v200, v26, v205, v200
	v_fma_f32 v200, v34, v206, v200
	v_lshlrev_b32_e32 v204, 16, v107
	v_lshlrev_b32_e32 v205, 16, v115
	v_lshlrev_b32_e32 v206, 16, v123
	v_fma_f32 v201, v70, v204, v98
	v_fma_f32 v201, v82, v205, v201
	v_fma_f32 v201, v90, v206, v201
	v_mul_f32_e32 v208, 0xbfb8aa3b, v200
	v_exp_f32_e32 v208, v208
	s_nop 0
	v_add_f32_e32 v209, 1.0, v208
	v_div_scale_f32 v210, s[26:27], v209, v209, v200
	v_rcp_f32_e32 v211, v210
	s_nop 0
	v_fma_f32 v212, -v210, v211, 1.0
	v_fmac_f32_e32 v211, v212, v211
	v_div_scale_f32 v213, vcc, v200, v209, v200
	v_mul_f32_e32 v214, v213, v211
	v_fma_f32 v215, -v210, v214, v213
	v_fmac_f32_e32 v214, v215, v211
	v_fma_f32 v210, -v210, v214, v213
	v_div_fmas_f32 v210, v210, v211, v214
	v_div_fixup_f32 v210, v210, v209, v200
	v_mul_f32_e32 v216, v210, v201
	v_and_b32_e32 v204, 0xffff0000, v103
	v_and_b32_e32 v205, 0xffff0000, v111
	v_and_b32_e32 v206, 0xffff0000, v119
	v_fma_f32 v200, v11, v204, v43
	v_fma_f32 v200, v27, v205, v200
	v_fma_f32 v200, v35, v206, v200
	v_and_b32_e32 v204, 0xffff0000, v107
	v_and_b32_e32 v205, 0xffff0000, v115
	v_and_b32_e32 v206, 0xffff0000, v123
	v_fma_f32 v201, v71, v204, v99
	v_fma_f32 v201, v83, v205, v201
	v_fma_f32 v201, v91, v206, v201
	v_mul_f32_e32 v208, 0xbfb8aa3b, v200
	v_exp_f32_e32 v208, v208
	s_nop 0
	v_add_f32_e32 v209, 1.0, v208
	v_div_scale_f32 v210, s[26:27], v209, v209, v200
	v_rcp_f32_e32 v211, v210
	s_nop 0
	v_fma_f32 v212, -v210, v211, 1.0
	v_fmac_f32_e32 v211, v212, v211
	v_div_scale_f32 v213, vcc, v200, v209, v200
	v_mul_f32_e32 v214, v213, v211
	v_fma_f32 v215, -v210, v214, v213
	v_fmac_f32_e32 v214, v215, v211
	v_fma_f32 v210, -v210, v214, v213
	v_div_fmas_f32 v210, v210, v211, v214
	v_div_fixup_f32 v210, v210, v209, v200
	v_mul_f32_e32 v217, v210, v201
	v_bfe_u32 v220, v216, 16, 1
	v_bfe_u32 v221, v217, 16, 1
	v_add3_u32 v220, v216, v220, s10
	v_add3_u32 v221, v217, v221, s10
	v_lshrrev_b32_e32 v220, 16, v220
	v_and_or_b32 v199, v221, s11, v220
	v_mov_b32_e32 v192, v224
	v_cmp_gt_u32_e32 vcc, s7, v192
	v_mov_b32_e32 v193, 0x1600
	v_mul_lo_u32 v193, v190, v193
	v_add_u32_e32 v180, v193, v227
	v_mov_b32_e32 v181, 0
	v_lshl_add_u64 v[180:181], v[180:181], 0, s[30:31]
	s_and_saveexec_b64 s[26:27], vcc
	global_store_dwordx4 v[180:181], v[196:199], off
	s_mov_b64 exec, s[26:27]
	s_nop 1
	s_waitcnt vmcnt(7)
; DI void ffn_fixup_phase(const Args& A, int wave_s, int l, int rows) {
;     ...
;         const int c8 = (e % 352) * 8, rs = e / 352, side = rs & 1, kb = rs >> 1;
;         const int R = kb * 64 + (side ? 63 : 0);
;         bool first, last;
;         if (R < NLAT) { first = (R & 8191) == 0; last = (R & 8191) == 8191; } else { first = ((R - NLAT) & 255) == 0; last = ((R - NLAT) & 255) == 255; }
;         const v4u z = {0u, 0u, 0u, 0u};
;         const bf16* pp = side ? UB + (size_t)((kb * 4 + 2) * 2) * 2816 : UB + (size_t)(((kb - 1) * 4 + 3) * 2) * 2816;
;         const bf16* pc = UB + (size_t)((kb * 4 + (side ? 3 : 0)) * 2) * 2816;
;         const bf16* pn = side ? UB + (size_t)(((kb + 1) * 4 + 0) * 2) * 2816 : UB + (size_t)((kb * 4 + 1) * 2) * 2816;
;         const bool zp = (!side) && first, zn = side && last;
;         const v4u a0 = zp ? z : *(const v4u*)(pp + c8), a1 = *(const v4u*)(pc + c8), a2 = zn ? z : *(const v4u*)(pn + c8);
;         const v4u b0 = zp ? z : *(const v4u*)(pp + 2816 + c8), b1 = *(const v4u*)(pc + 2816 + c8), b2 = zn ? z : *(const v4u*)(pn + 2816 + c8);
;         unsigned res[4];
; #pragma unroll
;         for (int q = 0; q < 4; ++q) {
;             float r2[2];
; #pragma unroll
;             for (int hlf = 0; hlf < 2; ++hlf) {
;                 const int i = c8 + 2 * q + hlf;
;                 const float ua0 = hlf ? __builtin_bit_cast(float, a0[q] & 0xffff0000u) : __builtin_bit_cast(float, a0[q] << 16);
;                 const float ua1 = hlf ? __builtin_bit_cast(float, a1[q] & 0xffff0000u) : __builtin_bit_cast(float, a1[q] << 16);
;                 const float ua2 = hlf ? __builtin_bit_cast(float, a2[q] & 0xffff0000u) : __builtin_bit_cast(float, a2[q] << 16);
;                 const float ub0 = hlf ? __builtin_bit_cast(float, b0[q] & 0xffff0000u) : __builtin_bit_cast(float, b0[q] << 16);
;                 const float ub1 = hlf ? __builtin_bit_cast(float, b1[q] & 0xffff0000u) : __builtin_bit_cast(float, b1[q] << 16);
;                 const float ub2 = hlf ? __builtin_bit_cast(float, b2[q] & 0xffff0000u) : __builtin_bit_cast(float, b2[q] << 16);
;                 const float ya = cb[i] + ua0 * cw[i] + ua1 * cw[5632 + i] + ua2 * cw[2 * 5632 + i];
;                 const float yv = cb[2816 + i] + ub0 * cw[2816 + i] + ub1 * cw[5632 + 2816 + i] + ub2 * cw[2 * 5632 + 2816 + i];
;                 r2[hlf] = silu_f(ya) * yv;
;             }
	v_and_b32_e32 v188, 1, v230
	v_lshrrev_b32_e32 v190, 1, v230
	v_lshlrev_b32_e32 v190, 6, v190
	v_mad_u32_u24 v190, v188, 63, v190
	v_mov_b32_e32 v191, 0xff
	v_mov_b32_e32 v189, 0x1fff
	v_cmp_gt_u32_e32 vcc, 0x8000, v190
	s_nop 1
	v_cndmask_b32_e32 v191, v191, v189, vcc
	v_and_b32_e32 v189, v190, v191
	v_or_b32_e32 v192, v189, v188
	v_cmp_eq_u32_e32 vcc, 0, v192
	s_nop 1
	v_cndmask_b32_e64 v124, v124, 0, vcc
	v_cndmask_b32_e64 v125, v125, 0, vcc
	v_cndmask_b32_e64 v126, v126, 0, vcc
	v_cndmask_b32_e64 v127, v127, 0, vcc
	v_cndmask_b32_e64 v128, v128, 0, vcc
	v_cndmask_b32_e64 v129, v129, 0, vcc
	v_cndmask_b32_e64 v130, v130, 0, vcc
	v_cndmask_b32_e64 v131, v131, 0, vcc
	v_cmp_eq_u32_e64 s[26:27], v189, v191
	v_cmp_eq_u32_e32 vcc, 1, v188
	s_nop 1
	s_and_b64 vcc, vcc, s[26:27]
	s_nop 1
	v_cndmask_b32_e64 v140, v140, 0, vcc
	v_cndmask_b32_e64 v141, v141, 0, vcc
	v_cndmask_b32_e64 v142, v142, 0, vcc
	v_cndmask_b32_e64 v143, v143, 0, vcc
	v_cndmask_b32_e64 v144, v144, 0, vcc
	v_cndmask_b32_e64 v145, v145, 0, vcc
	v_cndmask_b32_e64 v146, v146, 0, vcc
	v_cndmask_b32_e64 v147, v147, 0, vcc
	v_lshlrev_b32_e32 v204, 16, v124
	v_lshlrev_b32_e32 v205, 16, v132
	v_lshlrev_b32_e32 v206, 16, v140
	v_fma_f32 v200, v4, v204, v36
	v_fma_f32 v200, v12, v205, v200
	v_fma_f32 v200, v28, v206, v200
	v_lshlrev_b32_e32 v204, 16, v128
	v_lshlrev_b32_e32 v205, 16, v136
	v_lshlrev_b32_e32 v206, 16, v144
	v_fma_f32 v201, v64, v204, v92
	v_fma_f32 v201, v72, v205, v201
	v_fma_f32 v201, v84, v206, v201
	v_mul_f32_e32 v208, 0xbfb8aa3b, v200
	v_exp_f32_e32 v208, v208
	s_nop 0
	v_add_f32_e32 v209, 1.0, v208
	v_div_scale_f32 v210, s[26:27], v209, v209, v200
	v_rcp_f32_e32 v211, v210
	s_nop 0
	v_fma_f32 v212, -v210, v211, 1.0
	v_fmac_f32_e32 v211, v212, v211
	v_div_scale_f32 v213, vcc, v200, v209, v200
	v_mul_f32_e32 v214, v213, v211
	v_fma_f32 v215, -v210, v214, v213
	v_fmac_f32_e32 v214, v215, v211
	v_fma_f32 v210, -v210, v214, v213
	v_div_fmas_f32 v210, v210, v211, v214
	v_div_fixup_f32 v210, v210, v209, v200
	v_mul_f32_e32 v216, v210, v201
	v_and_b32_e32 v204, 0xffff0000, v124
	v_and_b32_e32 v205, 0xffff0000, v132
	v_and_b32_e32 v206, 0xffff0000, v140
	v_fma_f32 v200, v5, v204, v37
	v_fma_f32 v200, v13, v205, v200
	v_fma_f32 v200, v29, v206, v200
	v_and_b32_e32 v204, 0xffff0000, v128
	v_and_b32_e32 v205, 0xffff0000, v136
	v_and_b32_e32 v206, 0xffff0000, v144
	v_fma_f32 v201, v65, v204, v93
	v_fma_f32 v201, v73, v205, v201
	v_fma_f32 v201, v85, v206, v201
	v_mul_f32_e32 v208, 0xbfb8aa3b, v200
	v_exp_f32_e32 v208, v208
	s_nop 0
	v_add_f32_e32 v209, 1.0, v208
	v_div_scale_f32 v210, s[26:27], v209, v209, v200
	v_rcp_f32_e32 v211, v210
	s_nop 0
	v_fma_f32 v212, -v210, v211, 1.0
	v_fmac_f32_e32 v211, v212, v211
	v_div_scale_f32 v213, vcc, v200, v209, v200
	v_mul_f32_e32 v214, v213, v211
	v_fma_f32 v215, -v210, v214, v213
	v_fmac_f32_e32 v214, v215, v211
	v_fma_f32 v210, -v210, v214, v213
	v_div_fmas_f32 v210, v210, v211, v214
	v_div_fixup_f32 v210, v210, v209, v200
	v_mul_f32_e32 v217, v210, v201
	v_bfe_u32 v220, v216, 16, 1
	v_bfe_u32 v221, v217, 16, 1
	v_add3_u32 v220, v216, v220, s10
	v_add3_u32 v221, v217, v221, s10
	v_lshrrev_b32_e32 v220, 16, v220
	v_and_or_b32 v196, v221, s11, v220
	v_lshlrev_b32_e32 v204, 16, v125
	v_lshlrev_b32_e32 v205, 16, v133
	v_lshlrev_b32_e32 v206, 16, v141
	v_fma_f32 v200, v6, v204, v38
	v_fma_f32 v200, v14, v205, v200
	v_fma_f32 v200, v30, v206, v200
	v_lshlrev_b32_e32 v204, 16, v129
	v_lshlrev_b32_e32 v205, 16, v137
	v_lshlrev_b32_e32 v206, 16, v145
	v_fma_f32 v201, v66, v204, v94
	v_fma_f32 v201, v74, v205, v201
	v_fma_f32 v201, v86, v206, v201
	v_mul_f32_e32 v208, 0xbfb8aa3b, v200
	v_exp_f32_e32 v208, v208
	s_nop 0
	v_add_f32_e32 v209, 1.0, v208
	v_div_scale_f32 v210, s[26:27], v209, v209, v200
	v_rcp_f32_e32 v211, v210
	s_nop 0
	v_fma_f32 v212, -v210, v211, 1.0
	v_fmac_f32_e32 v211, v212, v211
	v_div_scale_f32 v213, vcc, v200, v209, v200
	v_mul_f32_e32 v214, v213, v211
	v_fma_f32 v215, -v210, v214, v213
	v_fmac_f32_e32 v214, v215, v211
	v_fma_f32 v210, -v210, v214, v213
	v_div_fmas_f32 v210, v210, v211, v214
	v_div_fixup_f32 v210, v210, v209, v200
	v_mul_f32_e32 v216, v210, v201
	v_and_b32_e32 v204, 0xffff0000, v125
	v_and_b32_e32 v205, 0xffff0000, v133
	v_and_b32_e32 v206, 0xffff0000, v141
	v_fma_f32 v200, v7, v204, v39
	v_fma_f32 v200, v15, v205, v200
	v_fma_f32 v200, v31, v206, v200
	v_and_b32_e32 v204, 0xffff0000, v129
	v_and_b32_e32 v205, 0xffff0000, v137
	v_and_b32_e32 v206, 0xffff0000, v145
	v_fma_f32 v201, v67, v204, v95
	v_fma_f32 v201, v75, v205, v201
	v_fma_f32 v201, v87, v206, v201
	v_mul_f32_e32 v208, 0xbfb8aa3b, v200
	v_exp_f32_e32 v208, v208
	s_nop 0
	v_add_f32_e32 v209, 1.0, v208
	v_div_scale_f32 v210, s[26:27], v209, v209, v200
	v_rcp_f32_e32 v211, v210
	s_nop 0
	v_fma_f32 v212, -v210, v211, 1.0
	v_fmac_f32_e32 v211, v212, v211
	v_div_scale_f32 v213, vcc, v200, v209, v200
	v_mul_f32_e32 v214, v213, v211
	v_fma_f32 v215, -v210, v214, v213
	v_fmac_f32_e32 v214, v215, v211
	v_fma_f32 v210, -v210, v214, v213
	v_div_fmas_f32 v210, v210, v211, v214
	v_div_fixup_f32 v210, v210, v209, v200
	v_mul_f32_e32 v217, v210, v201
	v_bfe_u32 v220, v216, 16, 1
	v_bfe_u32 v221, v217, 16, 1
	v_add3_u32 v220, v216, v220, s10
	v_add3_u32 v221, v217, v221, s10
	v_lshrrev_b32_e32 v220, 16, v220
	v_and_or_b32 v197, v221, s11, v220
	v_lshlrev_b32_e32 v204, 16, v126
	v_lshlrev_b32_e32 v205, 16, v134
	v_lshlrev_b32_e32 v206, 16, v142
	v_fma_f32 v200, v8, v204, v40
	v_fma_f32 v200, v24, v205, v200
	v_fma_f32 v200, v32, v206, v200
	v_lshlrev_b32_e32 v204, 16, v130
	v_lshlrev_b32_e32 v205, 16, v138
	v_lshlrev_b32_e32 v206, 16, v146
; DI unsigned pk2(float lo, float hi) { return f2bf(lo) | (f2bf(hi) << 16); }
; DI float silu_f(float x) { return x / (1.f + __expf(-x)); }
; DI void ffn_fixup_phase(const Args& A, int wave_s, int l, int rows) {
;     ...
;             for (int hlf = 0; hlf < 2; ++hlf) {
;                 const int i = c8 + 2 * q + hlf;
;                 const float ua0 = hlf ? __builtin_bit_cast(float, a0[q] & 0xffff0000u) : __builtin_bit_cast(float, a0[q] << 16);
;                 const float ua1 = hlf ? __builtin_bit_cast(float, a1[q] & 0xffff0000u) : __builtin_bit_cast(float, a1[q] << 16);
;                 const float ua2 = hlf ? __builtin_bit_cast(float, a2[q] & 0xffff0000u) : __builtin_bit_cast(float, a2[q] << 16);
;                 const float ub0 = hlf ? __builtin_bit_cast(float, b0[q] & 0xffff0000u) : __builtin_bit_cast(float, b0[q] << 16);
;                 const float ub1 = hlf ? __builtin_bit_cast(float, b1[q] & 0xffff0000u) : __builtin_bit_cast(float, b1[q] << 16);
;                 const float ub2 = hlf ? __builtin_bit_cast(float, b2[q] & 0xffff0000u) : __builtin_bit_cast(float, b2[q] << 16);
;                 const float ya = cb[i] + ua0 * cw[i] + ua1 * cw[5632 + i] + ua2 * cw[2 * 5632 + i];
;                 const float yv = cb[2816 + i] + ub0 * cw[2816 + i] + ub1 * cw[5632 + 2816 + i] + ub2 * cw[2 * 5632 + 2816 + i];
;                 r2[hlf] = silu_f(ya) * yv;
;             }
;             res[q] = pk2(r2[0], r2[1]);
;         }
;         v4u o; o.x = res[0]; o.y = res[1]; o.z = res[2]; o.w = res[3];
;         *(v4u*)(ACTF + (size_t)R * 2816 + c8) = o;
	v_fma_f32 v201, v68, v204, v96
	v_fma_f32 v201, v80, v205, v201
	v_fma_f32 v201, v88, v206, v201
	v_mul_f32_e32 v208, 0xbfb8aa3b, v200
	v_exp_f32_e32 v208, v208
	s_nop 0
	v_add_f32_e32 v209, 1.0, v208
	v_div_scale_f32 v210, s[26:27], v209, v209, v200
	v_rcp_f32_e32 v211, v210
	s_nop 0
	v_fma_f32 v212, -v210, v211, 1.0
	v_fmac_f32_e32 v211, v212, v211
	v_div_scale_f32 v213, vcc, v200, v209, v200
	v_mul_f32_e32 v214, v213, v211
	v_fma_f32 v215, -v210, v214, v213
	v_fmac_f32_e32 v214, v215, v211
	v_fma_f32 v210, -v210, v214, v213
	v_div_fmas_f32 v210, v210, v211, v214
	v_div_fixup_f32 v210, v210, v209, v200
	v_mul_f32_e32 v216, v210, v201
	v_and_b32_e32 v204, 0xffff0000, v126
	v_and_b32_e32 v205, 0xffff0000, v134
	v_and_b32_e32 v206, 0xffff0000, v142
	v_fma_f32 v200, v9, v204, v41
	v_fma_f32 v200, v25, v205, v200
	v_fma_f32 v200, v33, v206, v200
	v_and_b32_e32 v204, 0xffff0000, v130
	v_and_b32_e32 v205, 0xffff0000, v138
	v_and_b32_e32 v206, 0xffff0000, v146
	v_fma_f32 v201, v69, v204, v97
	v_fma_f32 v201, v81, v205, v201
	v_fma_f32 v201, v89, v206, v201
	v_mul_f32_e32 v208, 0xbfb8aa3b, v200
	v_exp_f32_e32 v208, v208
	s_nop 0
	v_add_f32_e32 v209, 1.0, v208
	v_div_scale_f32 v210, s[26:27], v209, v209, v200
	v_rcp_f32_e32 v211, v210
	s_nop 0
	v_fma_f32 v212, -v210, v211, 1.0
	v_fmac_f32_e32 v211, v212, v211
	v_div_scale_f32 v213, vcc, v200, v209, v200
	v_mul_f32_e32 v214, v213, v211
	v_fma_f32 v215, -v210, v214, v213
	v_fmac_f32_e32 v214, v215, v211
	v_fma_f32 v210, -v210, v214, v213
	v_div_fmas_f32 v210, v210, v211, v214
	v_div_fixup_f32 v210, v210, v209, v200
	v_mul_f32_e32 v217, v210, v201
	v_bfe_u32 v220, v216, 16, 1
	v_bfe_u32 v221, v217, 16, 1
	v_add3_u32 v220, v216, v220, s10
	v_add3_u32 v221, v217, v221, s10
	v_lshrrev_b32_e32 v220, 16, v220
	v_and_or_b32 v198, v221, s11, v220
	v_lshlrev_b32_e32 v204, 16, v127
	v_lshlrev_b32_e32 v205, 16, v135
	v_lshlrev_b32_e32 v206, 16, v143
	v_fma_f32 v200, v10, v204, v42
	v_fma_f32 v200, v26, v205, v200
	v_fma_f32 v200, v34, v206, v200
	v_lshlrev_b32_e32 v204, 16, v131
	v_lshlrev_b32_e32 v205, 16, v139
	v_lshlrev_b32_e32 v206, 16, v147
	v_fma_f32 v201, v70, v204, v98
	v_fma_f32 v201, v82, v205, v201
	v_fma_f32 v201, v90, v206, v201
	v_mul_f32_e32 v208, 0xbfb8aa3b, v200
	v_exp_f32_e32 v208, v208
	s_nop 0
	v_add_f32_e32 v209, 1.0, v208
	v_div_scale_f32 v210, s[26:27], v209, v209, v200
	v_rcp_f32_e32 v211, v210
	s_nop 0
	v_fma_f32 v212, -v210, v211, 1.0
	v_fmac_f32_e32 v211, v212, v211
	v_div_scale_f32 v213, vcc, v200, v209, v200
	v_mul_f32_e32 v214, v213, v211
	v_fma_f32 v215, -v210, v214, v213
	v_fmac_f32_e32 v214, v215, v211
	v_fma_f32 v210, -v210, v214, v213
	v_div_fmas_f32 v210, v210, v211, v214
	v_div_fixup_f32 v210, v210, v209, v200
	v_mul_f32_e32 v216, v210, v201
	v_and_b32_e32 v204, 0xffff0000, v127
	v_and_b32_e32 v205, 0xffff0000, v135
	v_and_b32_e32 v206, 0xffff0000, v143
	v_fma_f32 v200, v11, v204, v43
	v_fma_f32 v200, v27, v205, v200
	v_fma_f32 v200, v35, v206, v200
	v_and_b32_e32 v204, 0xffff0000, v131
	v_and_b32_e32 v205, 0xffff0000, v139
	v_and_b32_e32 v206, 0xffff0000, v147
	v_fma_f32 v201, v71, v204, v99
	v_fma_f32 v201, v83, v205, v201
	v_fma_f32 v201, v91, v206, v201
	v_mul_f32_e32 v208, 0xbfb8aa3b, v200
	v_exp_f32_e32 v208, v208
	s_nop 0
	v_add_f32_e32 v209, 1.0, v208
	v_div_scale_f32 v210, s[26:27], v209, v209, v200
	v_rcp_f32_e32 v211, v210
	s_nop 0
	v_fma_f32 v212, -v210, v211, 1.0
	v_fmac_f32_e32 v211, v212, v211
	v_div_scale_f32 v213, vcc, v200, v209, v200
	v_mul_f32_e32 v214, v213, v211
	v_fma_f32 v215, -v210, v214, v213
	v_fmac_f32_e32 v214, v215, v211
	v_fma_f32 v210, -v210, v214, v213
	v_div_fmas_f32 v210, v210, v211, v214
	v_div_fixup_f32 v210, v210, v209, v200
	v_mul_f32_e32 v217, v210, v201
	v_bfe_u32 v220, v216, 16, 1
	v_bfe_u32 v221, v217, 16, 1
	v_add3_u32 v220, v216, v220, s10
	v_add3_u32 v221, v217, v221, s10
	v_lshrrev_b32_e32 v220, 16, v220
	v_and_or_b32 v199, v221, s11, v220
	v_add_u32_e32 v192, 130944, v224
	v_cmp_gt_u32_e32 vcc, s7, v192
	v_mov_b32_e32 v193, 0x1600
	v_mul_lo_u32 v193, v190, v193
	v_add_u32_e32 v180, v193, v227
	v_mov_b32_e32 v181, 0
	v_lshl_add_u64 v[180:181], v[180:181], 0, s[30:31]
	s_and_saveexec_b64 s[26:27], vcc
	global_store_dwordx4 v[180:181], v[196:199], off
	s_mov_b64 exec, s[26:27]
	s_nop 1
	s_waitcnt vmcnt(2)
; DI void ffn_fixup_phase(const Args& A, int wave_s, int l, int rows) {
;     ...
;         const int c8 = (e % 352) * 8, rs = e / 352, side = rs & 1, kb = rs >> 1;
;         const int R = kb * 64 + (side ? 63 : 0);
;         bool first, last;
;         if (R < NLAT) { first = (R & 8191) == 0; last = (R & 8191) == 8191; } else { first = ((R - NLAT) & 255) == 0; last = ((R - NLAT) & 255) == 255; }
;         const v4u z = {0u, 0u, 0u, 0u};
;         const bf16* pp = side ? UB + (size_t)((kb * 4 + 2) * 2) * 2816 : UB + (size_t)(((kb - 1) * 4 + 3) * 2) * 2816;
;         const bf16* pc = UB + (size_t)((kb * 4 + (side ? 3 : 0)) * 2) * 2816;
;         const bf16* pn = side ? UB + (size_t)(((kb + 1) * 4 + 0) * 2) * 2816 : UB + (size_t)((kb * 4 + 1) * 2) * 2816;
;         const bool zp = (!side) && first, zn = side && last;
;         const v4u a0 = zp ? z : *(const v4u*)(pp + c8), a1 = *(const v4u*)(pc + c8), a2 = zn ? z : *(const v4u*)(pn + c8);
;         const v4u b0 = zp ? z : *(const v4u*)(pp + 2816 + c8), b1 = *(const v4u*)(pc + 2816 + c8), b2 = zn ? z : *(const v4u*)(pn + 2816 + c8);
;         unsigned res[4];
; #pragma unroll
;         for (int q = 0; q < 4; ++q) {
;             float r2[2];
; #pragma unroll
;             for (int hlf = 0; hlf < 2; ++hlf) {
;                 const int i = c8 + 2 * q + hlf;
;                 const float ua0 = hlf ? __builtin_bit_cast(float, a0[q] & 0xffff0000u) : __builtin_bit_cast(float, a0[q] << 16);
;                 const float ua1 = hlf ? __builtin_bit_cast(float, a1[q] & 0xffff0000u) : __builtin_bit_cast(float, a1[q] << 16);
;                 const float ua2 = hlf ? __builtin_bit_cast(float, a2[q] & 0xffff0000u) : __builtin_bit_cast(float, a2[q] << 16);
;                 const float ub0 = hlf ? __builtin_bit_cast(float, b0[q] & 0xffff0000u) : __builtin_bit_cast(float, b0[q] << 16);
;                 const float ub1 = hlf ? __builtin_bit_cast(float, b1[q] & 0xffff0000u) : __builtin_bit_cast(float, b1[q] << 16);
;                 const float ub2 = hlf ? __builtin_bit_cast(float, b2[q] & 0xffff0000u) : __builtin_bit_cast(float, b2[q] << 16);
;                 const float ya = cb[i] + ua0 * cw[i] + ua1 * cw[5632 + i] + ua2 * cw[2 * 5632 + i];
;                 const float yv = cb[2816 + i] + ub0 * cw[2816 + i] + ub1 * cw[5632 + 2816 + i] + ub2 * cw[2 * 5632 + 2816 + i];
;                 r2[hlf] = silu_f(ya) * yv;
;             }
	v_and_b32_e32 v188, 1, v231
	v_lshrrev_b32_e32 v190, 1, v231
	v_lshlrev_b32_e32 v190, 6, v190
	v_mad_u32_u24 v190, v188, 63, v190
	v_mov_b32_e32 v191, 0xff
	v_mov_b32_e32 v189, 0x1fff
	v_cmp_gt_u32_e32 vcc, 0x8000, v190
	s_nop 1
	v_cndmask_b32_e32 v191, v191, v189, vcc
	v_and_b32_e32 v189, v190, v191
	v_or_b32_e32 v192, v189, v188
	v_cmp_eq_u32_e32 vcc, 0, v192
	s_nop 1
	v_cndmask_b32_e64 v148, v148, 0, vcc
	v_cndmask_b32_e64 v149, v149, 0, vcc
	v_cndmask_b32_e64 v150, v150, 0, vcc
	v_cndmask_b32_e64 v151, v151, 0, vcc
	v_cndmask_b32_e64 v152, v152, 0, vcc
	v_cndmask_b32_e64 v153, v153, 0, vcc
	v_cndmask_b32_e64 v154, v154, 0, vcc
	v_cndmask_b32_e64 v155, v155, 0, vcc
	v_cmp_eq_u32_e64 s[26:27], v189, v191
	v_cmp_eq_u32_e32 vcc, 1, v188
	s_nop 1
	s_and_b64 vcc, vcc, s[26:27]
	s_nop 1
	v_cndmask_b32_e64 v168, v168, 0, vcc
	v_cndmask_b32_e64 v169, v169, 0, vcc
	v_cndmask_b32_e64 v170, v170, 0, vcc
	v_cndmask_b32_e64 v171, v171, 0, vcc
	v_cndmask_b32_e64 v172, v172, 0, vcc
	v_cndmask_b32_e64 v173, v173, 0, vcc
	v_cndmask_b32_e64 v174, v174, 0, vcc
	v_cndmask_b32_e64 v175, v175, 0, vcc
	v_lshlrev_b32_e32 v204, 16, v148
	v_lshlrev_b32_e32 v205, 16, v156
	v_lshlrev_b32_e32 v206, 16, v168
	v_fma_f32 v200, v4, v204, v36
	v_fma_f32 v200, v12, v205, v200
	v_fma_f32 v200, v28, v206, v200
	v_lshlrev_b32_e32 v204, 16, v152
	v_lshlrev_b32_e32 v205, 16, v164
	v_lshlrev_b32_e32 v206, 16, v172
	v_fma_f32 v201, v64, v204, v92
	v_fma_f32 v201, v72, v205, v201
	v_fma_f32 v201, v84, v206, v201
	v_mul_f32_e32 v208, 0xbfb8aa3b, v200
	v_exp_f32_e32 v208, v208
	s_nop 0
	v_add_f32_e32 v209, 1.0, v208
	v_div_scale_f32 v210, s[26:27], v209, v209, v200
	v_rcp_f32_e32 v211, v210
	s_nop 0
	v_fma_f32 v212, -v210, v211, 1.0
	v_fmac_f32_e32 v211, v212, v211
	v_div_scale_f32 v213, vcc, v200, v209, v200
	v_mul_f32_e32 v214, v213, v211
	v_fma_f32 v215, -v210, v214, v213
	v_fmac_f32_e32 v214, v215, v211
	v_fma_f32 v210, -v210, v214, v213
	v_div_fmas_f32 v210, v210, v211, v214
	v_div_fixup_f32 v210, v210, v209, v200
	v_mul_f32_e32 v216, v210, v201
	v_and_b32_e32 v204, 0xffff0000, v148
	v_and_b32_e32 v205, 0xffff0000, v156
	v_and_b32_e32 v206, 0xffff0000, v168
	v_fma_f32 v200, v5, v204, v37
	v_fma_f32 v200, v13, v205, v200
	v_fma_f32 v200, v29, v206, v200
	v_and_b32_e32 v204, 0xffff0000, v152
	v_and_b32_e32 v205, 0xffff0000, v164
	v_and_b32_e32 v206, 0xffff0000, v172
	v_fma_f32 v201, v65, v204, v93
	v_fma_f32 v201, v73, v205, v201
	v_fma_f32 v201, v85, v206, v201
	v_mul_f32_e32 v208, 0xbfb8aa3b, v200
	v_exp_f32_e32 v208, v208
	s_nop 0
	v_add_f32_e32 v209, 1.0, v208
	v_div_scale_f32 v210, s[26:27], v209, v209, v200
	v_rcp_f32_e32 v211, v210
	s_nop 0
	v_fma_f32 v212, -v210, v211, 1.0
	v_fmac_f32_e32 v211, v212, v211
	v_div_scale_f32 v213, vcc, v200, v209, v200
	v_mul_f32_e32 v214, v213, v211
	v_fma_f32 v215, -v210, v214, v213
	v_fmac_f32_e32 v214, v215, v211
	v_fma_f32 v210, -v210, v214, v213
	v_div_fmas_f32 v210, v210, v211, v214
	v_div_fixup_f32 v210, v210, v209, v200
	v_mul_f32_e32 v217, v210, v201
	v_bfe_u32 v220, v216, 16, 1
	v_bfe_u32 v221, v217, 16, 1
	v_add3_u32 v220, v216, v220, s10
	v_add3_u32 v221, v217, v221, s10
	v_lshrrev_b32_e32 v220, 16, v220
	v_and_or_b32 v196, v221, s11, v220
	v_lshlrev_b32_e32 v204, 16, v149
	v_lshlrev_b32_e32 v205, 16, v157
	v_lshlrev_b32_e32 v206, 16, v169
	v_fma_f32 v200, v6, v204, v38
	v_fma_f32 v200, v14, v205, v200
	v_fma_f32 v200, v30, v206, v200
	v_lshlrev_b32_e32 v204, 16, v153
	v_lshlrev_b32_e32 v205, 16, v165
	v_lshlrev_b32_e32 v206, 16, v173
	v_fma_f32 v201, v66, v204, v94
	v_fma_f32 v201, v74, v205, v201
	v_fma_f32 v201, v86, v206, v201
	v_mul_f32_e32 v208, 0xbfb8aa3b, v200
	v_exp_f32_e32 v208, v208
	s_nop 0
	v_add_f32_e32 v209, 1.0, v208
	v_div_scale_f32 v210, s[26:27], v209, v209, v200
	v_rcp_f32_e32 v211, v210
	s_nop 0
	v_fma_f32 v212, -v210, v211, 1.0
	v_fmac_f32_e32 v211, v212, v211
	v_div_scale_f32 v213, vcc, v200, v209, v200
	v_mul_f32_e32 v214, v213, v211
	v_fma_f32 v215, -v210, v214, v213
	v_fmac_f32_e32 v214, v215, v211
	v_fma_f32 v210, -v210, v214, v213
	v_div_fmas_f32 v210, v210, v211, v214
	v_div_fixup_f32 v210, v210, v209, v200
	v_mul_f32_e32 v216, v210, v201
	v_and_b32_e32 v204, 0xffff0000, v149
	v_and_b32_e32 v205, 0xffff0000, v157
	v_and_b32_e32 v206, 0xffff0000, v169
	v_fma_f32 v200, v7, v204, v39
	v_fma_f32 v200, v15, v205, v200
	v_fma_f32 v200, v31, v206, v200
	v_and_b32_e32 v204, 0xffff0000, v153
	v_and_b32_e32 v205, 0xffff0000, v165
	v_and_b32_e32 v206, 0xffff0000, v173
	v_fma_f32 v201, v67, v204, v95
	v_fma_f32 v201, v75, v205, v201
	v_fma_f32 v201, v87, v206, v201
	v_mul_f32_e32 v208, 0xbfb8aa3b, v200
	v_exp_f32_e32 v208, v208
	s_nop 0
	v_add_f32_e32 v209, 1.0, v208
	v_div_scale_f32 v210, s[26:27], v209, v209, v200
	v_rcp_f32_e32 v211, v210
	s_nop 0
	v_fma_f32 v212, -v210, v211, 1.0
	v_fmac_f32_e32 v211, v212, v211
	v_div_scale_f32 v213, vcc, v200, v209, v200
	v_mul_f32_e32 v214, v213, v211
	v_fma_f32 v215, -v210, v214, v213
	v_fmac_f32_e32 v214, v215, v211
; DI unsigned pk2(float lo, float hi) { return f2bf(lo) | (f2bf(hi) << 16); }
; DI float silu_f(float x) { return x / (1.f + __expf(-x)); }
; DI void ffn_fixup_phase(const Args& A, int wave_s, int l, int rows) {
;     ...
;             for (int hlf = 0; hlf < 2; ++hlf) {
;                 const int i = c8 + 2 * q + hlf;
;                 const float ua0 = hlf ? __builtin_bit_cast(float, a0[q] & 0xffff0000u) : __builtin_bit_cast(float, a0[q] << 16);
;                 const float ua1 = hlf ? __builtin_bit_cast(float, a1[q] & 0xffff0000u) : __builtin_bit_cast(float, a1[q] << 16);
;                 const float ua2 = hlf ? __builtin_bit_cast(float, a2[q] & 0xffff0000u) : __builtin_bit_cast(float, a2[q] << 16);
;                 const float ub0 = hlf ? __builtin_bit_cast(float, b0[q] & 0xffff0000u) : __builtin_bit_cast(float, b0[q] << 16);
;                 const float ub1 = hlf ? __builtin_bit_cast(float, b1[q] & 0xffff0000u) : __builtin_bit_cast(float, b1[q] << 16);
;                 const float ub2 = hlf ? __builtin_bit_cast(float, b2[q] & 0xffff0000u) : __builtin_bit_cast(float, b2[q] << 16);
;                 const float ya = cb[i] + ua0 * cw[i] + ua1 * cw[5632 + i] + ua2 * cw[2 * 5632 + i];
;                 const float yv = cb[2816 + i] + ub0 * cw[2816 + i] + ub1 * cw[5632 + 2816 + i] + ub2 * cw[2 * 5632 + 2816 + i];
;                 r2[hlf] = silu_f(ya) * yv;
;             }
;             res[q] = pk2(r2[0], r2[1]);
;         }
;         v4u o; o.x = res[0]; o.y = res[1]; o.z = res[2]; o.w = res[3];
;         *(v4u*)(ACTF + (size_t)R * 2816 + c8) = o;
	v_fma_f32 v210, -v210, v214, v213
	v_div_fmas_f32 v210, v210, v211, v214
	v_div_fixup_f32 v210, v210, v209, v200
	v_mul_f32_e32 v217, v210, v201
	v_bfe_u32 v220, v216, 16, 1
	v_bfe_u32 v221, v217, 16, 1
	v_add3_u32 v220, v216, v220, s10
	v_add3_u32 v221, v217, v221, s10
	v_lshrrev_b32_e32 v220, 16, v220
	v_and_or_b32 v197, v221, s11, v220
	v_lshlrev_b32_e32 v204, 16, v150
	v_lshlrev_b32_e32 v205, 16, v158
	v_lshlrev_b32_e32 v206, 16, v170
	v_fma_f32 v200, v8, v204, v40
	v_fma_f32 v200, v24, v205, v200
	v_fma_f32 v200, v32, v206, v200
	v_lshlrev_b32_e32 v204, 16, v154
	v_lshlrev_b32_e32 v205, 16, v166
	v_lshlrev_b32_e32 v206, 16, v174
	v_fma_f32 v201, v68, v204, v96
	v_fma_f32 v201, v80, v205, v201
	v_fma_f32 v201, v88, v206, v201
	v_mul_f32_e32 v208, 0xbfb8aa3b, v200
	v_exp_f32_e32 v208, v208
	s_nop 0
	v_add_f32_e32 v209, 1.0, v208
	v_div_scale_f32 v210, s[26:27], v209, v209, v200
	v_rcp_f32_e32 v211, v210
	s_nop 0
	v_fma_f32 v212, -v210, v211, 1.0
	v_fmac_f32_e32 v211, v212, v211
	v_div_scale_f32 v213, vcc, v200, v209, v200
	v_mul_f32_e32 v214, v213, v211
	v_fma_f32 v215, -v210, v214, v213
	v_fmac_f32_e32 v214, v215, v211
	v_fma_f32 v210, -v210, v214, v213
	v_div_fmas_f32 v210, v210, v211, v214
	v_div_fixup_f32 v210, v210, v209, v200
	v_mul_f32_e32 v216, v210, v201
	v_and_b32_e32 v204, 0xffff0000, v150
	v_and_b32_e32 v205, 0xffff0000, v158
	v_and_b32_e32 v206, 0xffff0000, v170
	v_fma_f32 v200, v9, v204, v41
	v_fma_f32 v200, v25, v205, v200
	v_fma_f32 v200, v33, v206, v200
	v_and_b32_e32 v204, 0xffff0000, v154
	v_and_b32_e32 v205, 0xffff0000, v166
	v_and_b32_e32 v206, 0xffff0000, v174
	v_fma_f32 v201, v69, v204, v97
	v_fma_f32 v201, v81, v205, v201
	v_fma_f32 v201, v89, v206, v201
	v_mul_f32_e32 v208, 0xbfb8aa3b, v200
	v_exp_f32_e32 v208, v208
	s_nop 0
	v_add_f32_e32 v209, 1.0, v208
	v_div_scale_f32 v210, s[26:27], v209, v209, v200
	v_rcp_f32_e32 v211, v210
	s_nop 0
	v_fma_f32 v212, -v210, v211, 1.0
	v_fmac_f32_e32 v211, v212, v211
	v_div_scale_f32 v213, vcc, v200, v209, v200
	v_mul_f32_e32 v214, v213, v211
	v_fma_f32 v215, -v210, v214, v213
	v_fmac_f32_e32 v214, v215, v211
	v_fma_f32 v210, -v210, v214, v213
	v_div_fmas_f32 v210, v210, v211, v214
	v_div_fixup_f32 v210, v210, v209, v200
	v_mul_f32_e32 v217, v210, v201
	v_bfe_u32 v220, v216, 16, 1
	v_bfe_u32 v221, v217, 16, 1
	v_add3_u32 v220, v216, v220, s10
	v_add3_u32 v221, v217, v221, s10
	v_lshrrev_b32_e32 v220, 16, v220
	v_and_or_b32 v198, v221, s11, v220
	v_lshlrev_b32_e32 v204, 16, v151
	v_lshlrev_b32_e32 v205, 16, v159
	v_lshlrev_b32_e32 v206, 16, v171
	v_fma_f32 v200, v10, v204, v42
	v_fma_f32 v200, v26, v205, v200
	v_fma_f32 v200, v34, v206, v200
	v_lshlrev_b32_e32 v204, 16, v155
	v_lshlrev_b32_e32 v205, 16, v167
	v_lshlrev_b32_e32 v206, 16, v175
	v_fma_f32 v201, v70, v204, v98
	v_fma_f32 v201, v82, v205, v201
	v_fma_f32 v201, v90, v206, v201
	v_mul_f32_e32 v208, 0xbfb8aa3b, v200
	v_exp_f32_e32 v208, v208
	s_nop 0
	v_add_f32_e32 v209, 1.0, v208
	v_div_scale_f32 v210, s[26:27], v209, v209, v200
	v_rcp_f32_e32 v211, v210
	s_nop 0
	v_fma_f32 v212, -v210, v211, 1.0
	v_fmac_f32_e32 v211, v212, v211
	v_div_scale_f32 v213, vcc, v200, v209, v200
	v_mul_f32_e32 v214, v213, v211
	v_fma_f32 v215, -v210, v214, v213
	v_fmac_f32_e32 v214, v215, v211
	v_fma_f32 v210, -v210, v214, v213
	v_div_fmas_f32 v210, v210, v211, v214
	v_div_fixup_f32 v210, v210, v209, v200
	v_mul_f32_e32 v216, v210, v201
	v_and_b32_e32 v204, 0xffff0000, v151
	v_and_b32_e32 v205, 0xffff0000, v159
	v_and_b32_e32 v206, 0xffff0000, v171
	v_fma_f32 v200, v11, v204, v43
	v_fma_f32 v200, v27, v205, v200
	v_fma_f32 v200, v35, v206, v200
	v_and_b32_e32 v204, 0xffff0000, v155
	v_and_b32_e32 v205, 0xffff0000, v167
	v_and_b32_e32 v206, 0xffff0000, v175
	v_fma_f32 v201, v71, v204, v99
	v_fma_f32 v201, v83, v205, v201
	v_fma_f32 v201, v91, v206, v201
	v_mul_f32_e32 v208, 0xbfb8aa3b, v200
	v_exp_f32_e32 v208, v208
	s_nop 0
	v_add_f32_e32 v209, 1.0, v208
	v_div_scale_f32 v210, s[26:27], v209, v209, v200
	v_rcp_f32_e32 v211, v210
	s_nop 0
	v_fma_f32 v212, -v210, v211, 1.0
	v_fmac_f32_e32 v211, v212, v211
	v_div_scale_f32 v213, vcc, v200, v209, v200
	v_mul_f32_e32 v214, v213, v211
	v_fma_f32 v215, -v210, v214, v213
	v_fmac_f32_e32 v214, v215, v211
	v_fma_f32 v210, -v210, v214, v213
	v_div_fmas_f32 v210, v210, v211, v214
	v_div_fixup_f32 v210, v210, v209, v200
	v_mul_f32_e32 v217, v210, v201
	v_bfe_u32 v220, v216, 16, 1
	v_bfe_u32 v221, v217, 16, 1
	v_add3_u32 v220, v216, v220, s10
	v_add3_u32 v221, v217, v221, s10
	v_lshrrev_b32_e32 v220, 16, v220
	v_and_or_b32 v199, v221, s11, v220
	v_add_u32_e32 v192, 261888, v224
	v_cmp_gt_u32_e32 vcc, s7, v192
	v_mov_b32_e32 v193, 0x1600
	v_mul_lo_u32 v193, v190, v193
	v_add_u32_e32 v180, v193, v227
	v_mov_b32_e32 v181, 0
	v_lshl_add_u64 v[180:181], v[180:181], 0, s[30:31]
	s_and_saveexec_b64 s[26:27], vcc
	global_store_dwordx4 v[180:181], v[196:199], off
	s_mov_b64 exec, s[26:27]
	s_nop 1
.Lfix_f_done:
	s_mov_b64 s[10:11], exec
